# seam2 counter + static s_setprio 1 for waves 4-7 during hgrn recurrence
# baseline (speedup 1.0000x reference)
; #define LAS __attribute__((address_space(3)))
; #define LBAR() asm volatile("s_waitcnt lgkmcnt(0)\n\ts_barrier" ::: "memory")
; #define HG_LOADG(c, hgv) do { const size_t tq_ = hbase + 64 * (c) + 16 * tt + l15; \
;         _Pragma("unroll") for (int j = 0; j < 4; ++j) hgv[j] = *(const u32x2*)(HG + tq_ * 128 + 16 * (4 * vh + j) + 4 * q4); } while (0)
; #define HG_PREP1(gq) do { float r0_ = 1.f, r1_ = 1.f; \
;         _Pragma("unroll") for (int i = 0; i < 8; ++i) { r0_ *= f16lo(gq[i]); r1_ *= f16hi(gq[i]); } \
;         *(LAS f32x2*)(TOT + seg * 128 + 2 * kp) = (f32x2){__log2f(r0_), __log2f(r1_)}; } while (0)
;     const int tid = threadIdx.x, lane = tid & 63, w = __builtin_amdgcn_readfirstlane(tid >> 6), l15 = lane & 15, q4 = lane >> 4;
;     constexpr int P = 136, IMGB = 52224;
;     LAS u16* SB = (LAS u16*)(lds + 104448); LAS float* TOT = (LAS float*)(lds + 139264); LAS float* DFB = (LAS float*)(lds + 143360); LAS float* SSQ = (LAS float*)(lds + 146432);
;     f32x4 S[8];
; #pragma unroll
;     for (int i = 0; i < 8; ++i) S[i] = (f32x4){0.f, 0.f, 0.f, 0.f};
;     const int kp = lane, seg = w, tt = (w < 4) ? (w >> 1) : 3 - ((w - 4) >> 1), vh = w & 1;
;     const size_t tok0 = (size_t)b * SEQ, hbase = (size_t)(b * 8 + h) * SEQ;
;     unsigned gq0[8], qq0[8], gq1[8], qq1[8]; u32x4 vv0[2], vv1[2]; u32x2 hg0[4], hg1[4];
;     f32x4 O[4]; float sqp = 0.f;
; #pragma unroll
;     for (int j = 0; j < 4; ++j) O[j] = (f32x4){0.f, 0.f, 0.f, 0.f};
;     ...
;     unsigned dacc_ = 0u;
;     LAS unsigned char* STG = lds + 146944;
;     f32x4 nwv[4];
; #pragma unroll
;     for (int j = 0; j < 4; ++j) nwv[j] = *(const f32x4*)(nw + 16 * (4 * vh + j) + 4 * q4);
;     HG_LOAD(0, gq0, qq0, vv0); HG_LOADG(0, hg0); HG_LOADG(0, hg1); if (tid < 128) SSQ[tid] = 1.0f; HG_PREP1(gq0); LBAR(); HG_PREP2(0, gq0, qq0, vv0);
.LBB0_492:
	s_and_b64 vcc, exec, s[0:1]
	s_cbranch_vccz .LBB0_532
	v_readfirstlane_b32 s98, v188
	s_nop 3
	s_cmp_lt_u32 s98, 0x100
	s_cbranch_scc1 .Lhg_prio_skip
	s_setprio 1
.Lhg_prio_skip:
	s_and_b32 s0, s2, 7
	s_ashr_i32 s4, s2, 3
	s_add_u32 s16, s78, 0xa000000
	v_readfirstlane_b32 s22, v188
	s_addc_u32 s17, s79, 0
	s_lshr_b32 s28, s22, 6
	s_add_i32 s5, s28, -4
	s_lshr_b32 s5, s5, 1
	s_lshr_b32 s1, s22, 7
	s_sub_i32 s5, 3, s5
	s_cmpk_lt_u32 s22, 0x100
	s_cselect_b32 s26, s1, s5
	s_waitcnt lgkmcnt(0)
	s_lshl_b32 s71, s0, 11
	s_lshl_b32 s0, s0, 3
	s_add_i32 s0, s0, s4
	v_mov_b32_e32 v69, 0
	s_ashr_i32 s1, s0, 31
	s_bfe_u32 s27, s22, 0x10006
	s_waitcnt vmcnt(0)
	v_and_b32_e32 v32, 48, v188
	v_mov_b32_e32 v33, v69
	s_mov_b32 s61, 0
	v_lshl_add_u64 v[0:1], s[66:67], 0, v[32:33]
	s_lshl_b32 s60, s27, 8
	s_lshl_b64 s[62:63], s[0:1], 11
	s_lshl_b32 s86, s28, 3
	s_lshl_b32 s0, s4, 7
	v_lshl_add_u64 v[16:17], v[0:1], 0, s[60:61]
	s_add_i32 s60, s86, s71
	s_ashr_i32 s1, s0, 31
	s_add_u32 s4, s62, s86
	s_addc_u32 s5, s63, 0
	s_lshl_b64 s[0:1], s[0:1], 1
	v_and_b32_e32 v35, 63, v188
	s_add_u32 s0, s78, s0
	v_lshlrev_b32_e32 v68, 2, v35
	s_addc_u32 s1, s79, s1
	global_load_dwordx4 v[0:3], v[16:17], off
	global_load_dwordx4 v[4:7], v[16:17], off offset:64
	global_load_dwordx4 v[8:11], v[16:17], off offset:128
	global_load_dwordx4 v[12:15], v[16:17], off offset:192
	v_lshl_add_u64 v[16:17], s[78:79], 0, v[68:69]
	s_mov_b64 s[6:7], 0x6000000
	s_add_u32 s18, s0, 0x4000000
	v_lshl_add_u64 v[70:71], v[16:17], 0, s[6:7]
	s_addc_u32 s19, s1, 0
	s_lshl_b64 s[0:1], s[4:5], 8
	v_lshl_add_u64 v[72:73], s[18:19], 0, v[68:69]
	v_lshl_add_u64 v[16:17], v[70:71], 0, s[0:1]
	s_lshl_b64 s[0:1], s[60:61], 11
	v_lshl_add_u64 v[18:19], v[72:73], 0, s[0:1]
	s_movk_i32 s0, 0x1000
	v_add_co_u32_e32 v20, vcc, s0, v18
	s_movk_i32 s0, 0x2000
	s_nop 0
	v_addc_co_u32_e32 v21, vcc, 0, v19, vcc
	v_add_co_u32_e32 v22, vcc, s0, v18
	s_movk_i32 s0, 0x3000
	s_nop 0
	v_addc_co_u32_e32 v23, vcc, 0, v19, vcc
	global_load_dword v51, v[22:23], off offset:-4096
	global_load_dword v50, v[22:23], off
	global_load_dword v39, v[22:23], off offset:2048
	v_add_co_u32_e32 v22, vcc, s0, v18
	s_mov_b64 s[0:1], 0x8000000
	s_nop 0
	v_addc_co_u32_e32 v23, vcc, 0, v19, vcc
	global_load_dword v31, v[16:17], off
	global_load_dword v38, v[16:17], off offset:256
	global_load_dword v30, v[16:17], off offset:512
	global_load_dword v29, v[16:17], off offset:768
	global_load_dword v28, v[16:17], off offset:1024
	global_load_dword v27, v[16:17], off offset:1280
	global_load_dword v26, v[16:17], off offset:1536
	global_load_dword v25, v[16:17], off offset:1792
	global_load_dword v56, v[18:19], off
	global_load_dword v55, v[18:19], off offset:2048
	global_load_dword v54, v[20:21], off offset:2048
	global_load_dword v53, v[22:23], off
	global_load_dword v52, v[22:23], off offset:2048
	v_lshlrev_b32_e32 v16, 3, v188
	v_and_b32_e32 v48, 0x78, v16
	v_lshlrev_b32_e32 v68, 1, v48
	v_lshl_add_u64 v[16:17], s[78:79], 0, v[68:69]
	v_lshrrev_b32_e32 v93, 4, v188
	v_add_u32_e32 v33, 0x200, v188
	s_lshl_b32 s20, s26, 4
	v_lshl_add_u64 v[74:75], v[16:17], 0, s[0:1]
	v_or_b32_e32 v16, s62, v93
	v_mov_b32_e32 v17, s63
	v_lshrrev_b32_e32 v68, 4, v33
	s_ashr_i32 s21, s20, 31
	v_lshlrev_b64 v[18:19], 8, v[16:17]
	v_or_b32_e32 v16, s62, v68
	s_add_u32 s0, s62, s20
	v_and_b32_e32 v34, 15, v188
	v_lshl_add_u64 v[36:37], v[74:75], 0, v[18:19]
	v_lshlrev_b64 v[16:17], 8, v[16:17]
	s_addc_u32 s1, s63, s21
	v_lshl_add_u64 v[40:41], v[74:75], 0, v[16:17]
	global_load_dwordx4 v[20:23], v[36:37], off
	global_load_dwordx4 v[16:19], v[40:41], off
	v_or_b32_e32 v36, s0, v34
	v_mov_b32_e32 v37, s1
	v_bfe_u32 v24, v188, 4, 2
	v_lshlrev_b64 v[36:37], 8, v[36:37]
	v_lshl_add_u64 v[40:41], s[16:17], 0, v[36:37]
	v_lshlrev_b32_e32 v36, 3, v24
	v_mov_b32_e32 v37, v69
	v_lshl_add_u64 v[40:41], v[40:41], 0, v[36:37]
	s_lshl_b32 s24, s27, 7
	s_mov_b32 s25, s61
	v_lshl_add_u64 v[40:41], v[40:41], 0, s[24:25]
	global_load_dwordx2 v[84:85], v[40:41], off
	global_load_dwordx2 v[82:83], v[40:41], off offset:32
	global_load_dwordx2 v[78:79], v[40:41], off offset:64
	global_load_dwordx2 v[76:77], v[40:41], off offset:96
	s_movk_i32 s0, 0x80
	v_writelane_b32 v248, s84, 4
	v_lshlrev_b32_e32 v37, 1, v35
	v_cmp_gt_u32_e32 vcc, s0, v188
	v_writelane_b32 v248, s85, 5
	s_and_saveexec_b64 s[0:1], vcc
	v_lshl_add_u32 v40, v188, 2, 0
	v_add_u32_e32 v40, 0x23c00, v40
	v_mov_b32_e32 v41, 1.0
	ds_write_b32 v40, v41
	s_or_b64 exec, exec, s[0:1]
	s_waitcnt vmcnt(17)
	v_cvt_f32_f16_e32 v40, v38
	v_cvt_f32_f16_e32 v42, v31
	v_cvt_f32_f16_sdwa v41, v38 dst_sel:DWORD dst_unused:UNUSED_PAD src0_sel:WORD_1
	v_cvt_f32_f16_sdwa v43, v31 dst_sel:DWORD dst_unused:UNUSED_PAD src0_sel:WORD_1
	s_waitcnt vmcnt(16)
	v_cvt_f32_f16_sdwa v45, v30 dst_sel:DWORD dst_unused:UNUSED_PAD src0_sel:WORD_1
	v_cvt_f32_f16_e32 v44, v30
	s_waitcnt vmcnt(15)
	v_cvt_f32_f16_sdwa v47, v29 dst_sel:DWORD dst_unused:UNUSED_PAD src0_sel:WORD_1
	v_cvt_f32_f16_e32 v46, v29
	s_waitcnt vmcnt(14)
	v_cvt_f32_f16_sdwa v67, v28 dst_sel:DWORD dst_unused:UNUSED_PAD src0_sel:WORD_1
	v_cvt_f32_f16_e32 v66, v28
	s_waitcnt vmcnt(13)
	v_cvt_f32_f16_sdwa v81, v27 dst_sel:DWORD dst_unused:UNUSED_PAD src0_sel:WORD_1
	v_cvt_f32_f16_e32 v80, v27
	s_waitcnt vmcnt(12)
	v_cvt_f32_f16_sdwa v87, v26 dst_sel:DWORD dst_unused:UNUSED_PAD src0_sel:WORD_1
	v_cvt_f32_f16_e32 v86, v26
	s_waitcnt vmcnt(11)
	v_cvt_f32_f16_sdwa v89, v25 dst_sel:DWORD dst_unused:UNUSED_PAD src0_sel:WORD_1
	v_cvt_f32_f16_e32 v88, v25
	v_mul_f32_e32 v25, v40, v42
	v_mul_f32_e32 v26, v41, v43
	v_mul_f32_e32 v25, v25, v44
	v_mul_f32_e32 v26, v26, v45
	v_mul_f32_e32 v25, v25, v46
	v_mul_f32_e32 v26, v26, v47
	v_mul_f32_e32 v25, v25, v66
	v_mul_f32_e32 v26, v26, v67
	v_mul_f32_e32 v25, v25, v80
	v_mul_f32_e32 v26, v26, v81
	v_mul_f32_e32 v25, v25, v86
	v_mul_f32_e32 v26, v26, v87
	v_mul_f32_e32 v25, v25, v88
	v_mul_f32_e32 v27, v26, v89
	v_log_f32_e32 v26, v25
	v_log_f32_e32 v27, v27
	s_lshl_b32 s0, s28, 9
	s_add_i32 s1, 0, 0x22000
	s_add_i32 s0, s1, s0
	v_lshlrev_b32_e32 v49, 2, v37
	v_add_u32_e32 v158, s0, v49
	ds_write_b64 v158, v[26:27]
	v_add_u32_e32 v159, s1, v49
	s_waitcnt lgkmcnt(0)
	s_barrier
	ds_read2st64_b64 v[58:61], v159 offset1:1
	ds_read2st64_b64 v[62:65], v159 offset0:2 offset1:3
	s_lshl_b32 s52, s27, 6
	s_cmp_lt_u32 s22, 64
	s_cselect_b64 s[64:65], -1, 0
	s_waitcnt lgkmcnt(1)
	v_add_f32_e32 v59, 0, v59
	v_lshlrev_b32_e32 v38, 2, v24
	s_cmpk_gt_u32 s22, 0x7f
	v_cndmask_b32_e64 v24, v59, 0, s[64:65]
	v_add_f32_e32 v25, v61, v24
	s_cselect_b64 s[0:1], -1, 0
	v_lshlrev_b32_e32 v118, 16, v39
	v_and_b32_e32 v119, 0xffff0000, v39
	v_add_f32_e32 v39, 0, v58
	s_cmpk_gt_u32 s22, 0xbf
	v_cndmask_b32_e64 v24, v24, v25, s[0:1]
	v_lshlrev_b32_e32 v112, 16, v50
	v_and_b32_e32 v113, 0xffff0000, v50
	v_cndmask_b32_e64 v50, v39, 0, s[64:65]
	s_waitcnt lgkmcnt(0)
	v_add_f32_e32 v25, v63, v24
	s_cselect_b64 s[4:5], -1, 0
	v_lshlrev_b32_e32 v102, 16, v51
	v_and_b32_e32 v103, 0xffff0000, v51
	v_add_f32_e32 v51, v60, v50
	v_cndmask_b32_e64 v28, v24, v25, s[4:5]
	ds_read2st64_b64 v[24:27], v159 offset0:4 offset1:5
	v_cndmask_b32_e64 v50, v50, v51, s[0:1]
	s_waitcnt vmcnt(6)
	v_lshlrev_b32_e32 v130, 16, v52
	v_and_b32_e32 v131, 0xffff0000, v52
	v_add_f32_e32 v52, v62, v50
	s_cmpk_gt_u32 s22, 0xff
	v_cndmask_b32_e64 v50, v50, v52, s[4:5]
	v_add_f32_e32 v29, v65, v28
	s_cselect_b64 s[6:7], -1, 0
	v_add_f32_e32 v51, v59, v61
	v_add_f32_e32 v52, v64, v50
	s_cmpk_gt_u32 s22, 0x13f
	v_cndmask_b32_e64 v57, v28, v29, s[6:7]
	ds_read2st64_b64 v[28:31], v159 offset0:6 offset1:7
	v_add_f32_e32 v51, v51, v63
	v_cndmask_b32_e64 v52, v50, v52, s[6:7]
	s_waitcnt lgkmcnt(1)
	v_add_f32_e32 v90, v25, v57
	s_cselect_b64 s[8:9], -1, 0
	v_add_f32_e32 v50, v51, v65
	v_add_f32_e32 v51, v24, v52
	s_cmpk_gt_u32 s22, 0x17f
	v_cndmask_b32_e64 v57, v57, v90, s[8:9]
	v_cndmask_b32_e64 v51, v52, v51, s[8:9]
	v_add_f32_e32 v90, v27, v57
	s_cselect_b64 s[10:11], -1, 0
	v_add_f32_e32 v52, v26, v51
	s_cmpk_gt_u32 s22, 0x1bf
	v_cndmask_b32_e64 v57, v57, v90, s[10:11]
	v_cndmask_b32_e64 v51, v51, v52, s[10:11]
	s_waitcnt lgkmcnt(0)
	v_add_f32_e32 v90, v29, v57
	s_cselect_b64 s[12:13], -1, 0
	v_add_f32_e32 v52, v28, v51
	s_cmpk_gt_u32 s22, 0x1ff
	v_cndmask_b32_e64 v92, v57, v90, s[12:13]
	v_add_f32_e32 v39, v39, v60
	v_cndmask_b32_e64 v51, v51, v52, s[12:13]
	v_add_f32_e32 v132, v31, v92
	s_cselect_b64 s[14:15], -1, 0
	v_add_f32_e32 v39, v39, v62
	v_add_f32_e32 v52, v30, v51
	s_mul_i32 s23, s28, 0x440
	v_lshlrev_b32_e32 v124, 16, v53
	v_and_b32_e32 v125, 0xffff0000, v53
	v_add_f32_e32 v39, v39, v64
	v_cndmask_b32_e64 v53, v92, v132, s[14:15]
	v_cndmask_b32_e64 v51, v51, v52, s[14:15]
	s_lshl_b32 s25, s23, 1
	v_sub_f32_e32 v51, v51, v39
	v_sub_f32_e32 v59, v53, v50
	s_add_i32 s23, s25, 0
	v_min_f32_e32 v52, 0x42e60000, v51
	v_min_f32_e32 v53, 0x42e60000, v59
	s_cmp_gt_u32 s22, 63
	s_mov_b32 s22, 0x42e60000
	v_exp_f32_e32 v52, v52
	v_exp_f32_e32 v53, v53
	v_min_f32_e64 v51, -v51, s22
	v_exp_f32_e32 v58, v51
	v_min_f32_e64 v51, -v59, s22
	v_rcp_f32_e32 v90, v42
	v_rcp_f32_e32 v91, v43
	v_exp_f32_e32 v59, v51
	v_lshlrev_b32_e32 v94, 16, v56
	v_and_b32_e32 v95, 0xffff0000, v56
	v_pk_add_f32 v[56:57], v[42:43], 1.0 op_sel_hi:[1,0] neg_lo:[1,0] neg_hi:[1,0]
	v_rcp_f32_e32 v96, v40
	v_rcp_f32_e32 v97, v41
	v_pk_mul_f32 v[42:43], v[52:53], v[42:43]
	v_lshlrev_b32_e32 v98, 16, v55
	v_and_b32_e32 v99, 0xffff0000, v55
	v_pk_add_f32 v[100:101], v[40:41], 1.0 op_sel_hi:[1,0] neg_lo:[1,0] neg_hi:[1,0]
	v_pk_mul_f32 v[40:41], v[42:43], v[40:41]
	v_rcp_f32_e32 v104, v44
	v_rcp_f32_e32 v105, v45
	v_pk_mul_f32 v[52:53], v[42:43], v[94:95]
	v_pk_mul_f32 v[42:43], v[40:41], v[98:99]
	v_lshl_add_u32 v160, v37, 1, s23
	v_cvt_pk_bf16_f32 v51, v52, v53
	v_pk_mul_f32 v[52:53], v[90:91], v[58:59]
	v_cvt_pk_bf16_f32 v42, v42, v43
	ds_write2_b32 v160, v51, v42 offset1:68
	v_pk_mul_f32 v[42:43], v[96:97], v[52:53]
	v_lshlrev_b32_e32 v108, 16, v54
	v_and_b32_e32 v109, 0xffff0000, v54
	v_rcp_f32_e32 v54, v46
	v_rcp_f32_e32 v55, v47
	v_pk_mul_f32 v[56:57], v[56:57], v[52:53]
	v_pk_mul_f32 v[52:53], v[100:101], v[42:43]
	v_pk_mul_f32 v[40:41], v[40:41], v[44:45]
	v_pk_add_f32 v[106:107], v[44:45], 1.0 op_sel_hi:[1,0] neg_lo:[1,0] neg_hi:[1,0]
	v_cvt_pk_bf16_f32 v56, v56, v57
	v_cvt_pk_bf16_f32 v51, v52, v53
	v_add_u32_e32 v52, 0x4400, v160
	v_pk_mul_f32 v[44:45], v[40:41], v[102:103]
	v_pk_mul_f32 v[42:43], v[104:105], v[42:43]
	ds_write2_b32 v52, v56, v51 offset1:68
	v_cvt_pk_bf16_f32 v51, v44, v45
	v_pk_mul_f32 v[44:45], v[106:107], v[42:43]
	v_pk_mul_f32 v[40:41], v[40:41], v[46:47]
	v_rcp_f32_e32 v114, v66
	v_rcp_f32_e32 v115, v67
	v_cvt_pk_bf16_f32 v53, v44, v45
	v_pk_mul_f32 v[44:45], v[40:41], v[108:109]
	v_pk_add_f32 v[110:111], v[46:47], 1.0 op_sel_hi:[1,0] neg_lo:[1,0] neg_hi:[1,0]
	v_cvt_pk_bf16_f32 v44, v44, v45
	v_pk_mul_f32 v[42:43], v[54:55], v[42:43]
	ds_write2_b32 v160, v51, v44 offset0:136 offset1:204
	v_pk_mul_f32 v[44:45], v[110:111], v[42:43]
	v_rcp_f32_e32 v120, v80
	v_rcp_f32_e32 v121, v81
	v_cvt_pk_bf16_f32 v44, v44, v45
	v_pk_mul_f32 v[40:41], v[40:41], v[66:67]
	v_pk_add_f32 v[116:117], v[66:67], 1.0 op_sel_hi:[1,0] neg_lo:[1,0] neg_hi:[1,0]
	ds_write2_b32 v52, v53, v44 offset0:136 offset1:204
	v_pk_mul_f32 v[44:45], v[40:41], v[112:113]
	v_pk_mul_f32 v[42:43], v[114:115], v[42:43]
	v_cvt_pk_bf16_f32 v46, v44, v45
	v_pk_mul_f32 v[44:45], v[116:117], v[42:43]
	v_pk_mul_f32 v[40:41], v[40:41], v[80:81]
	v_rcp_f32_e32 v126, v86
	v_rcp_f32_e32 v127, v87
	v_cvt_pk_bf16_f32 v47, v44, v45
	v_pk_mul_f32 v[44:45], v[40:41], v[118:119]
	v_pk_add_f32 v[122:123], v[80:81], 1.0 op_sel_hi:[1,0] neg_lo:[1,0] neg_hi:[1,0]
	v_cvt_pk_bf16_f32 v44, v44, v45
	v_add_u32_e32 v51, 0x400, v160
	v_pk_mul_f32 v[42:43], v[120:121], v[42:43]
	ds_write2_b32 v51, v46, v44 offset0:16 offset1:84
	v_pk_mul_f32 v[44:45], v[122:123], v[42:43]
	v_add_u32_e32 v46, 0x4800, v160
	v_cvt_pk_bf16_f32 v44, v44, v45
	v_pk_mul_f32 v[40:41], v[40:41], v[86:87]
	v_pk_add_f32 v[128:129], v[86:87], 1.0 op_sel_hi:[1,0] neg_lo:[1,0] neg_hi:[1,0]
	ds_write2_b32 v46, v47, v44 offset0:16 offset1:84
	v_pk_mul_f32 v[44:45], v[40:41], v[124:125]
	v_pk_mul_f32 v[42:43], v[126:127], v[42:43]
	v_cvt_pk_bf16_f32 v47, v44, v45
	v_pk_mul_f32 v[44:45], v[128:129], v[42:43]
	v_pk_mul_f32 v[40:41], v[40:41], v[88:89]
	v_cvt_pk_bf16_f32 v52, v44, v45
	v_rcp_f32_e32 v44, v88
	v_rcp_f32_e32 v45, v89
	v_pk_mul_f32 v[40:41], v[40:41], v[130:131]
	s_nop 0
	v_cvt_pk_bf16_f32 v40, v40, v41
	ds_write2_b32 v51, v47, v40 offset0:152 offset1:220
	v_pk_mul_f32 v[40:41], v[44:45], v[42:43]
	v_pk_add_f32 v[42:43], v[88:89], 1.0 op_sel_hi:[1,0] neg_lo:[1,0] neg_hi:[1,0]
	s_nop 0
	v_pk_mul_f32 v[40:41], v[42:43], v[40:41]
	s_nop 0
	v_cvt_pk_bf16_f32 v40, v40, v41
	ds_write2_b32 v46, v52, v40 offset0:152 offset1:220
	s_cbranch_scc1 .LBB0_497
	v_add_f32_e32 v25, v50, v25
	v_add_f32_e32 v24, v39, v24
	v_add_f32_e32 v25, v25, v27
	v_add_f32_e32 v24, v24, v26
	v_add_f32_e32 v25, v25, v29
	v_add_f32_e32 v24, v24, v28
	v_add_f32_e32 v27, v25, v31
	v_add_f32_e32 v26, v24, v30
	v_exp_f32_e32 v24, v26
	v_exp_f32_e32 v25, v27
	v_lshl_add_u32 v28, v37, 2, 0
	v_add_u32_e32 v29, 0x23000, v28
	ds_write_b64 v29, v[24:25]
	v_sub_f32_e32 v24, v26, v39
	v_sub_f32_e32 v25, v27, v50
	v_exp_f32_e32 v24, v24
	v_exp_f32_e32 v25, v25
	v_exp_f32_e32 v26, v39
	v_exp_f32_e32 v27, v50
	v_add_u32_e32 v29, 0x23200, v28
	ds_write_b64 v29, v[24:25]
	v_add_u32_e32 v24, 0x23400, v28
	ds_write_b64 v24, v[26:27]

; #define LAS __attribute__((address_space(3)))
; #define LBAR() asm volatile("s_waitcnt lgkmcnt(0)\n\ts_barrier" ::: "memory")
;     ...
;     HG_COPY(31);
;     if (MODE & 8) { if (dacc_ == 0x12345678u) OA[tid] = (u16)dacc_; }
;     ...
;     if (blockIdx.x == 0 && tid == 448) ((LAS unsigned long long*)(lds + 163344))[10] = (unsigned long long)tacc_;
;     ...
;     LBAR();
.LBB0_531:
	ds_read_b128 v[0:3], v213
	ds_read_b128 v[4:7], v202
	s_or_b32 s1, s71, 0x7c0
	s_brev_b32 s0, 60
	s_waitcnt vmcnt(25)
	v_mov_b32_e32 v19, 0
	s_waitcnt lgkmcnt(1)
	v_lshlrev_b32_e32 v8, 16, v0
	v_and_b32_e32 v9, 0xffff0000, v0
	v_lshlrev_b32_e32 v10, 16, v1
	v_and_b32_e32 v11, 0xffff0000, v1
	ds_read_b32 v1, v168
	ds_read_b32 v15, v170
	ds_read_b32 v0, v174
	ds_read_b32 v14, v176
	v_lshlrev_b32_e32 v12, 16, v2
	v_and_b32_e32 v13, 0xffff0000, v2
	v_lshlrev_b32_e32 v16, 16, v3
	v_and_b32_e32 v17, 0xffff0000, v3
	v_or_b32_e32 v3, s1, v93
	s_waitcnt lgkmcnt(0)
	v_pk_add_f32 v[0:1], v[0:1], v[14:15]
	v_mov_b32_e32 v2, 0x358637bd
	v_pk_fma_f32 v[14:15], v[0:1], s[0:1], v[2:3] op_sel_hi:[1,0,0]
	s_mov_b32 s0, 0x800000
	v_mul_f32_e32 v0, 0x4b800000, v15
	v_cmp_gt_f32_e32 vcc, s0, v15
	v_lshlrev_b32_e32 v18, 11, v3
	s_waitcnt vmcnt(24)
	v_lshl_add_u64 v[20:21], v[80:81], 0, v[18:19]
	v_cndmask_b32_e32 v0, v15, v0, vcc
	v_rsq_f32_e32 v0, v0
	v_readlane_b32 s84, v248, 4
	v_readlane_b32 s85, v248, 5
	v_mul_f32_e32 v1, 0x45800000, v0
	v_cndmask_b32_e32 v18, v0, v1, vcc
	v_pk_mul_f32 v[0:1], v[18:19], v[8:9] op_sel_hi:[0,1]
	v_pk_mul_f32 v[2:3], v[18:19], v[10:11] op_sel_hi:[0,1]
	v_cvt_pk_bf16_f32 v0, v0, v1
	v_cvt_pk_bf16_f32 v1, v2, v3
	v_pk_mul_f32 v[2:3], v[18:19], v[12:13] op_sel_hi:[0,1]
	v_cvt_pk_bf16_f32 v2, v2, v3
	v_mul_f32_e32 v3, 0x4b800000, v14
	v_cmp_gt_f32_e32 vcc, s0, v14
	v_pk_mul_f32 v[8:9], v[18:19], v[16:17] op_sel_hi:[0,1]
	v_add_lshl_u32 v18, s1, v68, 11
	v_cndmask_b32_e32 v3, v14, v3, vcc
	v_rsq_f32_e32 v10, v3
	v_cvt_pk_bf16_f32 v3, v8, v9
	global_store_dwordx4 v[20:21], v[0:3], off
	s_nop 1
	v_mul_f32_e32 v0, 0x45800000, v10
	v_cndmask_b32_e32 v8, v10, v0, vcc
	v_lshlrev_b32_e32 v0, 16, v4
	v_and_b32_e32 v1, 0xffff0000, v4
	v_lshlrev_b32_e32 v2, 16, v5
	v_and_b32_e32 v3, 0xffff0000, v5
	v_pk_mul_f32 v[0:1], v[8:9], v[0:1] op_sel_hi:[0,1]
	v_pk_mul_f32 v[2:3], v[8:9], v[2:3] op_sel_hi:[0,1]
	v_cvt_pk_bf16_f32 v0, v0, v1
	v_cvt_pk_bf16_f32 v1, v2, v3
	v_lshlrev_b32_e32 v2, 16, v6
	v_and_b32_e32 v3, 0xffff0000, v6
	v_lshlrev_b32_e32 v4, 16, v7
	v_and_b32_e32 v5, 0xffff0000, v7
	v_pk_mul_f32 v[2:3], v[8:9], v[2:3] op_sel_hi:[0,1]
	v_pk_mul_f32 v[4:5], v[8:9], v[4:5] op_sel_hi:[0,1]
	v_cvt_pk_bf16_f32 v2, v2, v3
	v_cvt_pk_bf16_f32 v3, v4, v5
	v_lshl_add_u64 v[4:5], v[80:81], 0, v[18:19]
	global_store_dwordx4 v[4:5], v[0:3], off
	s_waitcnt lgkmcnt(0)
	s_barrier
	s_setprio 0
